# attention: first-half tile staging ds_writes interleaved with the p0 fma block
# baseline (speedup 1.0000x reference)
; #define SBAR() __builtin_amdgcn_sched_barrier(0)
; #define SLOAD(i, k0) do { sr_[i].vs0 = St::ld8(&Vh[(long)((k0) + sr) * LDK + sc]); sr_[i].vs1 = St::ld8(&Vh[(long)((k0) + 32 + sr) * LDK + sc]); \
;     sr_[i].ks0 = St::ld8(&Kh[(long)((k0) + sr) * LDK + sc]); sr_[i].ks1 = St::ld8(&Kh[(long)((k0) + 32 + sr) * LDK + sc]); } while (0)
; #define RESC(a) do { if (__any((a) < 1.f)) { if (hi == 0) al_l[r32] = (a); asm volatile("s_waitcnt lgkmcnt(0)" ::: "memory"); \
;     for (int d = 0; d < 4; ++d) for (int r = 0; r < 16; ++r) o[d][r] *= al_l[crow(r, hi)]; } } while (0)
; __device__ __forceinline__ void partialSM(f32x16& p0, f32x16& p1, float& m_reg, float& mn, float& alpha) {
;     ...
;   float mnC = -mn * C;
;   for (int r = 0; r < 16; ++r) p0[r] = fmaf(p0[r], C, mnC); for (int r = 0; r < 16; ++r) p1[r] = fmaf(p1[r], C, mnC);
;   for (int r = 0; r < 16; ++r) p0[r] = __builtin_amdgcn_exp2f(p0[r]);
; }
; __device__ __forceinline__ void finishSM(f32x16& p0, f32x16& p1, float alpha, float& l_reg, bf16x8& pa0, bf16x8& pa1, bf16x8& pa2, bf16x8& pa3) {
;   for (int r = 0; r < 16; ++r) p1[r] = __builtin_amdgcn_exp2f(p1[r]);
;   float ps = 0; for (int r = 0; r < 16; ++r) ps += p0[r]; for (int r = 0; r < 16; ++r) ps += p1[r];
;   { auto rr = __builtin_amdgcn_permlane32_swap(__float_as_uint(ps), __float_as_uint(ps), false, false);
;     ps = __uint_as_float(rr[0]) + __uint_as_float(rr[1]); }
;   l_reg = l_reg * alpha + ps;
;     ...
;   PK4(p0, 0, pa0); PK4(p0, 8, pa1); PK4(p1, 0, pa2); PK4(p1, 8, pa3);
; template <typename TQ>
; __device__ __forceinline__ void attn_dense_body(const TQ* __restrict__ Qb, const bf16* __restrict__ Kh, const bf16* __restrict__ Vh,
;                                                 unsigned short* __restrict__ Ob, int seq, char* lds, const int wave_s) {
;     ...
;     RESC(alB); __syncthreads();
;     SBAR(); qkt(pA0, pA1, K_lds, qr, r32, hi);
;     finishSM(pB0, pB1, alB, l_reg, pa0, pa1, pa2, pa3); SBAR();
;     if (SDEPTH == 1 || j + 3 < NT) SLOAD(SE, (j + 1 + SDEPTH) * KVBLK); SBAR();
.LBB0_579:
	v_xor_b32_e32 v189, 0x18000, v189
	v_xor_b32_e32 v199, 0x18000, v199
	v_xor_b32_e32 v192, 0x18000, v192
	v_xor_b32_e32 v191, 0x18000, v191
	v_mul_f32_e32 v207, 0xbe0293ee, v206
	ds_write_b128 v187, v[128:131]
	v_fmamk_f32 v80, v80, 0x3e0293ee, v207
	v_fmamk_f32 v81, v81, 0x3e0293ee, v207
	v_fmamk_f32 v82, v82, 0x3e0293ee, v207
	v_fmamk_f32 v83, v83, 0x3e0293ee, v207
	ds_write_b128 v187, v[136:139] offset:8192
	v_fmamk_f32 v84, v84, 0x3e0293ee, v207
	v_fmamk_f32 v85, v85, 0x3e0293ee, v207
	v_fmamk_f32 v86, v86, 0x3e0293ee, v207
	v_fmamk_f32 v87, v87, 0x3e0293ee, v207
	ds_write_b128 v185, v[132:135] offset:32768
	v_fmamk_f32 v88, v88, 0x3e0293ee, v207
	v_fmamk_f32 v89, v89, 0x3e0293ee, v207
	v_fmamk_f32 v90, v90, 0x3e0293ee, v207
	v_fmamk_f32 v91, v91, 0x3e0293ee, v207
	ds_write_b128 v185, v[140:143] offset:40960
	v_fmamk_f32 v92, v92, 0x3e0293ee, v207
	v_fmamk_f32 v93, v93, 0x3e0293ee, v207
	v_fmamk_f32 v94, v94, 0x3e0293ee, v207
	v_fmamk_f32 v95, v95, 0x3e0293ee, v207
	v_exp_f32_e32 v160, v80
	v_exp_f32_e32 v175, v81
	v_exp_f32_e32 v161, v82
	v_exp_f32_e32 v174, v83
	v_exp_f32_e32 v162, v84
	v_exp_f32_e32 v173, v85
	v_exp_f32_e32 v163, v86
	v_exp_f32_e32 v172, v87
	v_exp_f32_e32 v164, v88
	v_exp_f32_e32 v171, v89
	v_exp_f32_e32 v165, v90
	v_exp_f32_e32 v170, v91
	v_exp_f32_e32 v166, v92
	v_exp_f32_e32 v169, v93
	v_exp_f32_e32 v167, v94
	v_exp_f32_e32 v168, v95
	v_fmamk_f32 v216, v64, 0x3e0293ee, v207
	v_fmamk_f32 v217, v65, 0x3e0293ee, v207
	v_fmamk_f32 v218, v66, 0x3e0293ee, v207
	v_fmamk_f32 v219, v67, 0x3e0293ee, v207
	v_fmamk_f32 v224, v68, 0x3e0293ee, v207
	v_fmamk_f32 v209, v69, 0x3e0293ee, v207
	v_fmamk_f32 v210, v70, 0x3e0293ee, v207
	v_fmamk_f32 v211, v71, 0x3e0293ee, v207
	v_fmamk_f32 v212, v72, 0x3e0293ee, v207
	v_fmamk_f32 v213, v73, 0x3e0293ee, v207
	v_fmamk_f32 v214, v74, 0x3e0293ee, v207
	v_fmamk_f32 v215, v75, 0x3e0293ee, v207
	v_fmamk_f32 v208, v76, 0x3e0293ee, v207
	v_fmamk_f32 v225, v77, 0x3e0293ee, v207
	v_fmamk_f32 v226, v78, 0x3e0293ee, v207
	v_fmac_f32_e32 v207, 0x3e0293ee, v79
	s_waitcnt lgkmcnt(0)
	s_barrier
	ds_read_b128 v[64:67], v189 offset:32768
	ds_read_b128 v[68:71], v189 offset:40960
	ds_read_b128 v[228:231], v199 offset:32768
	ds_read_b128 v[232:235], v199 offset:40960
	ds_read_b128 v[240:243], v192 offset:32768
	ds_read_b128 v[244:247], v192 offset:40960
	v_exp_f32_e32 v221, v207
	s_waitcnt lgkmcnt(5)
	v_mfma_f32_32x32x16_bf16 v[80:95], v[64:67], v[112:115], 0
	v_add_f32_e32 v207, v175, v160
	v_add_f32_e32 v207, v161, v207
	v_add_f32_e32 v207, v174, v207
	v_add_f32_e32 v207, v162, v207
	v_add_f32_e32 v207, v173, v207
	v_add_f32_e32 v207, v163, v207
	v_add_f32_e32 v207, v172, v207
	s_waitcnt lgkmcnt(4)
	v_mfma_f32_32x32x16_bf16 v[64:79], v[68:71], v[112:115], 0
	v_add_f32_e32 v207, v164, v207
	v_add_f32_e32 v207, v171, v207
	v_add_f32_e32 v207, v165, v207
	v_add_f32_e32 v207, v170, v207
	v_exp_f32_e32 v194, v216
	v_add_f32_e32 v207, v166, v207
	v_exp_f32_e32 v195, v217
	s_waitcnt lgkmcnt(3)
	v_mfma_f32_32x32x16_bf16 v[80:95], v[228:231], v[108:111], v[80:95]
	v_add_f32_e32 v207, v169, v207
	v_exp_f32_e32 v196, v218
	v_add_f32_e32 v207, v167, v207
	v_exp_f32_e32 v197, v219
	v_add_f32_e32 v207, v168, v207
	v_exp_f32_e32 v216, v224
	v_add_f32_e32 v207, v194, v207
	s_waitcnt lgkmcnt(2)
	v_mfma_f32_32x32x16_bf16 v[64:79], v[232:235], v[108:111], v[64:79]
	ds_read_b128 v[228:231], v191 offset:32768
	ds_read_b128 v[232:235], v191 offset:40960
	v_exp_f32_e32 v209, v209
	v_add_f32_e32 v207, v195, v207
	v_exp_f32_e32 v210, v210
	v_add_f32_e32 v207, v196, v207
	v_exp_f32_e32 v211, v211
	v_add_f32_e32 v207, v197, v207
	s_waitcnt lgkmcnt(3)
	v_mfma_f32_32x32x16_bf16 v[80:95], v[240:243], v[120:123], v[80:95]
	v_exp_f32_e32 v212, v212
	v_add_f32_e32 v207, v216, v207
	v_exp_f32_e32 v213, v213
	v_add_f32_e32 v207, v209, v207
	v_exp_f32_e32 v214, v214
	v_add_f32_e32 v207, v210, v207
	v_exp_f32_e32 v215, v215
	s_waitcnt lgkmcnt(2)
	v_mfma_f32_32x32x16_bf16 v[64:79], v[244:247], v[120:123], v[64:79]
	ds_read_b128 v[240:243], v189 offset:32896
	ds_read_b128 v[244:247], v189 offset:41088
	v_add_f32_e32 v207, v211, v207
	v_exp_f32_e32 v217, v208
	v_add_f32_e32 v207, v212, v207
	v_exp_f32_e32 v218, v225
	v_add_f32_e32 v207, v213, v207
	v_exp_f32_e32 v219, v226
	s_waitcnt lgkmcnt(3)
	v_mfma_f32_32x32x16_bf16 v[80:95], v[228:231], v[124:127], v[80:95]
	v_add_f32_e32 v207, v214, v207
	v_add_f32_e32 v207, v215, v207
	v_add_f32_e32 v207, v217, v207
	v_add_f32_e32 v207, v218, v207
	v_add_f32_e32 v207, v219, v207
	v_add_f32_e32 v207, v221, v207
	s_waitcnt lgkmcnt(2)
	v_mfma_f32_32x32x16_bf16 v[64:79], v[232:235], v[124:127], v[64:79]
	ds_read_b128 v[228:231], v199 offset:32896
	ds_read_b128 v[232:235], v199 offset:41088
	s_waitcnt lgkmcnt(3)
	v_mfma_f32_32x32x16_bf16 v[80:95], v[240:243], v[116:119], v[80:95]
	s_waitcnt lgkmcnt(2)
	v_mfma_f32_32x32x16_bf16 v[64:79], v[244:247], v[116:119], v[64:79]
	ds_read_b128 v[240:243], v192 offset:32896
	ds_read_b128 v[244:247], v192 offset:41088
	s_waitcnt lgkmcnt(3)
	v_mfma_f32_32x32x16_bf16 v[80:95], v[228:231], v[104:107], v[80:95]
	s_waitcnt lgkmcnt(2)
	v_mfma_f32_32x32x16_bf16 v[64:79], v[232:235], v[104:107], v[64:79]
	ds_read_b128 v[228:231], v191 offset:32896
	ds_read_b128 v[232:235], v191 offset:41088
	s_waitcnt lgkmcnt(3)
	v_mfma_f32_32x32x16_bf16 v[80:95], v[240:243], v[100:103], v[80:95]
	s_waitcnt lgkmcnt(2)
	v_mfma_f32_32x32x16_bf16 v[64:79], v[244:247], v[100:103], v[64:79]
	v_cvt_pk_bf16_f32 v160, v160, v175
	v_cvt_pk_bf16_f32 v161, v161, v174
	v_cvt_pk_bf16_f32 v162, v162, v173
	v_cvt_pk_bf16_f32 v163, v163, v172
	v_cvt_pk_bf16_f32 v164, v164, v171
	v_cvt_pk_bf16_f32 v165, v165, v170
	s_waitcnt lgkmcnt(1)
	v_mfma_f32_32x32x16_bf16 v[80:95], v[228:231], v[96:99], v[80:95]
	v_cvt_pk_bf16_f32 v166, v166, v169
	v_cvt_pk_bf16_f32 v167, v167, v168
	v_cvt_pk_bf16_f32 v168, v194, v195
	v_cvt_pk_bf16_f32 v169, v196, v197
	v_cvt_pk_bf16_f32 v170, v216, v209
	v_cvt_pk_bf16_f32 v171, v210, v211
	v_cvt_pk_bf16_f32 v172, v212, v213
	s_waitcnt lgkmcnt(0)
	v_mfma_f32_32x32x16_bf16 v[64:79], v[232:235], v[96:99], v[64:79]
	v_cvt_pk_bf16_f32 v173, v214, v215
	v_cvt_pk_bf16_f32 v174, v217, v218
	v_cvt_pk_bf16_f32 v175, v219, v221
	s_add_i32 s50, s50, 2
	s_cmp_ge_u32 s50, s49
	s_cselect_b64 s[44:45], -1, 0
	s_and_b64 vcc, exec, s[44:45]
	s_cbranch_vccnz .Lattn_skip_loads
	global_load_dwordx4 v[128:131], v176, s[52:53]
	global_load_dwordx4 v[132:135], v176, s[52:53] offset:-512
	s_add_u32 s52, s52, 0x18000
	s_addc_u32 s53, s53, 0
	global_load_dwordx4 v[136:139], v176, s[52:53]
	global_load_dwordx4 v[140:143], v176, s[52:53] offset:-512
	s_add_u32 s52, s52, 0x18000
	s_addc_u32 s53, s53, 0

; __device__ __forceinline__ void partialSM(f32x16& p0, f32x16& p1, float& m_reg, float& mn, float& alpha) {
;     ...
;   if (__builtin_expect(__all(pmax - m_reg <= THR / SCALE), 1)) { mn = m_reg; alpha = 1.f; }
;   else { mn = fmaxf(m_reg, pmax); alpha = __builtin_amdgcn_exp2f((m_reg - mn) * C); m_reg = mn; }
.Lattn_slow_a:
	v_max_f32_e32 v160, v164, v160
	v_sub_f32_e32 v161, v164, v160
	v_mul_f32_e32 v161, 0x3e0293ee, v161
	v_exp_f32_e32 v161, v161
	s_waitcnt vmcnt(4)
	s_nop 0
	v_mov_b32_e32 v205, v161
	v_cmp_gt_f32_e32 vcc, 1.0, v205
	s_nop 4
	s_cbranch_vccz .Lattn_slow_a_end
	s_and_saveexec_b64 s[44:45], s[38:39]
	ds_write_b32 v181, v205 offset:128
	s_or_b64 exec, exec, s[44:45]
	s_waitcnt lgkmcnt(0)
	v_add_u32_e32 v161, s1, v180
	ds_read_b128 v[166:169], v161 offset:224
	ds_read_b128 v[170:173], v161 offset:192
	ds_read_b128 v[206:209], v161 offset:160
	ds_read_b128 v[210:213], v161 offset:128
	s_waitcnt lgkmcnt(3)
	v_pk_mul_f32 v[12:13], v[12:13], v[166:167]
	s_waitcnt lgkmcnt(2)
	v_pk_mul_f32 v[8:9], v[8:9], v[170:171]
	s_waitcnt lgkmcnt(1)
	v_pk_mul_f32 v[4:5], v[4:5], v[206:207]
	v_pk_mul_f32 v[14:15], v[14:15], v[168:169]
	v_pk_mul_f32 v[10:11], v[10:11], v[172:173]
	v_pk_mul_f32 v[6:7], v[6:7], v[208:209]
	s_waitcnt lgkmcnt(0)
	v_pk_mul_f32 v[2:3], v[2:3], v[212:213]
	v_pk_mul_f32 v[0:1], v[0:1], v[210:211]
	v_pk_mul_f32 v[60:61], v[60:61], v[166:167]
	v_pk_mul_f32 v[56:57], v[56:57], v[170:171]
	v_pk_mul_f32 v[52:53], v[52:53], v[206:207]
	v_pk_mul_f32 v[62:63], v[62:63], v[168:169]
	v_pk_mul_f32 v[58:59], v[58:59], v[172:173]
	v_pk_mul_f32 v[54:55], v[54:55], v[208:209]
	v_pk_mul_f32 v[50:51], v[50:51], v[212:213]
	v_pk_mul_f32 v[48:49], v[48:49], v[210:211]
	v_pk_mul_f32 v[44:45], v[44:45], v[166:167]
	v_pk_mul_f32 v[40:41], v[40:41], v[170:171]
	v_pk_mul_f32 v[36:37], v[36:37], v[206:207]
	v_pk_mul_f32 v[46:47], v[46:47], v[168:169]
	v_pk_mul_f32 v[42:43], v[42:43], v[172:173]
	v_pk_mul_f32 v[38:39], v[38:39], v[208:209]
	v_pk_mul_f32 v[34:35], v[34:35], v[212:213]
	v_pk_mul_f32 v[32:33], v[32:33], v[210:211]
	v_pk_mul_f32 v[28:29], v[28:29], v[166:167]
	v_pk_mul_f32 v[24:25], v[24:25], v[170:171]
	v_pk_mul_f32 v[20:21], v[20:21], v[206:207]
	v_pk_mul_f32 v[30:31], v[30:31], v[168:169]
	v_pk_mul_f32 v[26:27], v[26:27], v[172:173]
	v_pk_mul_f32 v[22:23], v[22:23], v[208:209]
	v_pk_mul_f32 v[18:19], v[18:19], v[212:213]
	v_pk_mul_f32 v[16:17], v[16:17], v[210:211]
